# v36 plus X3 epilogue DPP, X3 cseg reuse, PREP h-row load batching (all individually neutral)
# speedup vs baseline: 1.0017x; 1.0008x over previous
; __device__ __forceinline__ void phase_prep(const Args& a, LAS unsigned char* lds, int G) {
;     ...
;     for (int rg = blockIdx.x; rg < TR / 32; rg += G)
;     for (int jr = 0; jr < 4; ++jr) { const int r = rg * 32 + wid * 4 + jr;
;         const float* src = r >= ROW_X ? a.x + (size_t)(r - ROW_X) * DM : (r >= ROW_META ? a.meta + (size_t)(r - ROW_META) * DM : nullptr);
;         float s = 0.f;
; #pragma unroll
;         for (int j = 0; j < 8; ++j) { f32x4 v = src ? *(const f32x4*)(src + j * 256 + lane * 4) : (f32x4){0.f, 0.f, 0.f, 0.f};
;             u32x2 w; w.x = cvtpk(v[0], v[1]); w.y = cvtpk(v[2], v[3]); *(u32x2*)(HB + (size_t)r * DM + j * 256 + lane * 4) = w;
;             s += (v[0] * v[0] + v[1] * v[1]) + (v[2] * v[2] + v[3] * v[3]); }
;         s = wave_sum(s); if (lane == 0) ssq0[r] = s;
;     }
.LBB0_112:
	s_or_b64 exec, exec, s[0:1]
	s_waitcnt lgkmcnt(0)
	v_cmp_ne_u64_e64 s[4:5], 0, v[0:1]
	v_lshl_add_u64 v[40:41], v[0:1], 0, v[32:33]
	v_ashrrev_i32_e32 v37, 31, v36
	v_lshlrev_b64 v[2:3], 12, v[36:37]
	v_lshl_add_u64 v[38:39], v[34:35], 0, v[2:3]
	v_mov_b32_e32 v0, 0
	v_mov_b32_e32 v4, 0
	v_mov_b32_e32 v5, 0
	v_mov_b32_e32 v6, 0
	v_mov_b32_e32 v7, 0
	s_and_saveexec_b64 s[0:1], s[4:5]
	s_cbranch_execz .LBB0_114
	global_load_dwordx4 v[4:7], v[40:41], off
.LBB0_114:
	s_or_b64 exec, exec, s[0:1]
	v_mov_b32_e32 v1, 0
	v_mov_b32_e32 v2, 0
	v_mov_b32_e32 v3, 0
	s_and_saveexec_b64 s[0:1], s[4:5]
	s_cbranch_execz .LBB0_116
	global_load_dwordx4 v[0:3], v[40:41], off offset:1024
.LBB0_116:
	s_or_b64 exec, exec, s[0:1]
	v_mov_b32_e32 v8, 0
	v_mov_b32_e32 v12, 0
	v_mov_b32_e32 v13, 0
	v_mov_b32_e32 v14, 0
	v_mov_b32_e32 v15, 0
	s_and_saveexec_b64 s[0:1], s[4:5]
	s_cbranch_execz .LBB0_118
	global_load_dwordx4 v[12:15], v[40:41], off offset:2048
.LBB0_118:
	s_or_b64 exec, exec, s[0:1]
	v_mov_b32_e32 v9, 0
	v_mov_b32_e32 v10, 0
	v_mov_b32_e32 v11, 0
	s_and_saveexec_b64 s[0:1], s[4:5]
	s_cbranch_execz .LBB0_120
	global_load_dwordx4 v[8:11], v[40:41], off offset:3072
.LBB0_120:
	s_or_b64 exec, exec, s[0:1]
	v_mov_b32_e32 v16, 0
	v_mov_b32_e32 v20, 0
	v_mov_b32_e32 v21, 0
	v_mov_b32_e32 v22, 0
	v_mov_b32_e32 v23, 0
	s_and_saveexec_b64 s[0:1], s[4:5]
	s_cbranch_execz .LBB0_122
	v_add_co_u32_e32 v18, vcc, 0x1000, v40
	s_nop 1
	v_addc_co_u32_e32 v19, vcc, 0, v41, vcc
	global_load_dwordx4 v[20:23], v[18:19], off
.LBB0_122:
	s_or_b64 exec, exec, s[0:1]
	v_mov_b32_e32 v17, 0
	v_mov_b32_e32 v18, 0
	v_mov_b32_e32 v19, 0
	s_and_saveexec_b64 s[0:1], s[4:5]
	s_cbranch_execz .LBB0_124
	v_add_co_u32_e32 v16, vcc, 0x1000, v40
	s_nop 1
	v_addc_co_u32_e32 v17, vcc, 0, v41, vcc
	global_load_dwordx4 v[16:19], v[16:17], off offset:1024
.LBB0_124:
	s_or_b64 exec, exec, s[0:1]
	v_mov_b32_e32 v24, 0
	v_mov_b32_e32 v28, 0
	v_mov_b32_e32 v29, 0
	v_mov_b32_e32 v30, 0
	v_mov_b32_e32 v31, 0
	s_and_saveexec_b64 s[0:1], s[4:5]
	s_cbranch_execz .LBB0_126
	v_add_co_u32_e32 v26, vcc, 0x1000, v40
	s_nop 1
	v_addc_co_u32_e32 v27, vcc, 0, v41, vcc
	global_load_dwordx4 v[28:31], v[26:27], off offset:2048
.LBB0_126:
	s_or_b64 exec, exec, s[0:1]
	v_mov_b32_e32 v25, 0
	v_mov_b32_e32 v26, 0
	v_mov_b32_e32 v27, 0
	s_and_saveexec_b64 s[0:1], s[4:5]
	s_cbranch_execz .LBB0_128
	v_add_co_u32_e32 v24, vcc, 0x1000, v40
	s_nop 1
	v_addc_co_u32_e32 v25, vcc, 0, v41, vcc
	global_load_dwordx4 v[24:27], v[24:25], off offset:3072
.LBB0_128:
	s_or_b64 exec, exec, s[0:1]
	s_waitcnt vmcnt(0)
	v_cvt_pk_bf16_f32 v200, v4, v5
	v_cvt_pk_bf16_f32 v201, v6, v7
	global_store_dwordx2 v[38:39], v[200:201], off
	v_cvt_pk_bf16_f32 v202, v0, v1
	v_cvt_pk_bf16_f32 v203, v2, v3
	global_store_dwordx2 v[38:39], v[202:203], off offset:512
	v_cvt_pk_bf16_f32 v204, v12, v13
	v_cvt_pk_bf16_f32 v205, v14, v15
	global_store_dwordx2 v[38:39], v[204:205], off offset:1024
	v_cvt_pk_bf16_f32 v206, v8, v9
	v_cvt_pk_bf16_f32 v207, v10, v11
	global_store_dwordx2 v[38:39], v[206:207], off offset:1536
	v_cvt_pk_bf16_f32 v208, v20, v21
	v_cvt_pk_bf16_f32 v209, v22, v23
	global_store_dwordx2 v[38:39], v[208:209], off offset:2048
	v_cvt_pk_bf16_f32 v210, v16, v17
	v_cvt_pk_bf16_f32 v211, v18, v19
	global_store_dwordx2 v[38:39], v[210:211], off offset:2560
	v_cvt_pk_bf16_f32 v212, v28, v29
	v_cvt_pk_bf16_f32 v213, v30, v31
	global_store_dwordx2 v[38:39], v[212:213], off offset:3072
	v_mul_f32_e32 v1, v1, v1
	v_mul_f32_e32 v5, v5, v5
	v_fmac_f32_e32 v1, v0, v0
	v_mul_f32_e32 v0, v3, v3
	v_fmac_f32_e32 v5, v4, v4
	v_mul_f32_e32 v4, v7, v7
	v_fmac_f32_e32 v0, v2, v2
	v_fmac_f32_e32 v4, v6, v6
	v_add_f32_e32 v0, v1, v0
	v_mul_f32_e32 v1, v13, v13
	v_mul_f32_e32 v2, v15, v15
	v_add_f32_e32 v4, v5, v4
	v_fmac_f32_e32 v1, v12, v12
	v_fmac_f32_e32 v2, v14, v14
	v_add_f32_e32 v0, v4, v0
	v_add_f32_e32 v1, v1, v2
	v_add_f32_e32 v0, v0, v1
	v_mul_f32_e32 v1, v9, v9
	v_mul_f32_e32 v2, v11, v11
	v_fmac_f32_e32 v1, v8, v8
	v_fmac_f32_e32 v2, v10, v10
	v_add_f32_e32 v1, v1, v2
	v_add_f32_e32 v0, v0, v1
	v_mul_f32_e32 v1, v21, v21
	v_mul_f32_e32 v2, v23, v23
	v_fmac_f32_e32 v1, v20, v20
	v_fmac_f32_e32 v2, v22, v22
	v_add_f32_e32 v1, v1, v2
	v_add_f32_e32 v0, v0, v1
	v_mul_f32_e32 v1, v17, v17
	v_mul_f32_e32 v2, v19, v19
	v_fmac_f32_e32 v1, v16, v16
	v_fmac_f32_e32 v2, v18, v18
	v_add_f32_e32 v1, v1, v2
	v_add_f32_e32 v0, v0, v1
	v_mul_f32_e32 v1, v29, v29
	v_mul_f32_e32 v2, v31, v31
	v_fmac_f32_e32 v1, v28, v28
	v_fmac_f32_e32 v2, v30, v30
	v_add_f32_e32 v1, v1, v2
	v_add_f32_e32 v0, v0, v1
	v_mul_f32_e32 v1, v25, v25
	v_mul_f32_e32 v2, v27, v27
	v_fmac_f32_e32 v1, v24, v24
	v_fmac_f32_e32 v2, v26, v26
	v_add_f32_e32 v1, v1, v2
	v_add_f32_e32 v0, v0, v1
	ds_bpermute_b32 v1, v44, v0
	v_cvt_pk_bf16_f32 v2, v24, v25
	v_cvt_pk_bf16_f32 v3, v26, v27
	global_store_dwordx2 v[38:39], v[2:3], off offset:3584
	s_waitcnt lgkmcnt(0)
	v_add_f32_e32 v0, v0, v1
	ds_bpermute_b32 v1, v45, v0
	s_waitcnt lgkmcnt(0)
	v_add_f32_e32 v0, v0, v1
	ds_bpermute_b32 v1, v46, v0
	s_waitcnt lgkmcnt(0)
	v_add_f32_e32 v0, v0, v1
	ds_bpermute_b32 v1, v47, v0
	s_waitcnt lgkmcnt(0)
	v_add_f32_e32 v0, v0, v1
	ds_bpermute_b32 v1, v48, v0
	s_waitcnt lgkmcnt(0)
	v_add_f32_e32 v0, v0, v1
	ds_bpermute_b32 v1, v49, v0
	s_and_saveexec_b64 s[0:1], s[2:3]
	s_cbranch_execz .LBB0_130
	s_waitcnt lgkmcnt(0)
	v_add_f32_e32 v2, v0, v1
	v_lshl_add_u64 v[0:1], v[36:37], 2, s[6:7]
	global_store_dword v[0:1], v2, off

; __device__ __forceinline__ void phase_prep(const Args& a, LAS unsigned char* lds, int G) {
;     ...
;     for (int rg = blockIdx.x; rg < TR / 32; rg += G)
;     for (int jr = 0; jr < 4; ++jr) { const int r = rg * 32 + wid * 4 + jr;
;         const float* src = r >= ROW_X ? a.x + (size_t)(r - ROW_X) * DM : (r >= ROW_META ? a.meta + (size_t)(r - ROW_META) * DM : nullptr);
;         float s = 0.f;
; #pragma unroll
;         for (int j = 0; j < 8; ++j) { f32x4 v = src ? *(const f32x4*)(src + j * 256 + lane * 4) : (f32x4){0.f, 0.f, 0.f, 0.f};
;             u32x2 w; w.x = cvtpk(v[0], v[1]); w.y = cvtpk(v[2], v[3]); *(u32x2*)(HB + (size_t)r * DM + j * 256 + lane * 4) = w;
;             s += (v[0] * v[0] + v[1] * v[1]) + (v[2] * v[2] + v[3] * v[3]); }
;         s = wave_sum(s); if (lane == 0) ssq0[r] = s;
;     }
.LBB0_134:
	s_or_b64 exec, exec, s[0:1]
	s_waitcnt lgkmcnt(0)
	v_cmp_ne_u64_e64 s[4:5], 0, v[0:1]
	v_lshl_add_u64 v[42:43], v[0:1], 0, v[32:33]
	v_add_u32_e32 v38, 1, v36
	v_ashrrev_i32_e32 v39, 31, v38
	v_lshlrev_b64 v[2:3], 12, v[38:39]
	v_lshl_add_u64 v[40:41], v[34:35], 0, v[2:3]
	v_mov_b32_e32 v0, 0
	v_mov_b32_e32 v4, 0
	v_mov_b32_e32 v5, 0
	v_mov_b32_e32 v6, 0
	v_mov_b32_e32 v7, 0
	s_and_saveexec_b64 s[0:1], s[4:5]
	s_cbranch_execz .LBB0_136
	global_load_dwordx4 v[4:7], v[42:43], off
.LBB0_136:
	s_or_b64 exec, exec, s[0:1]
	v_mov_b32_e32 v1, 0
	v_mov_b32_e32 v2, 0
	v_mov_b32_e32 v3, 0
	s_and_saveexec_b64 s[0:1], s[4:5]
	s_cbranch_execz .LBB0_138
	global_load_dwordx4 v[0:3], v[42:43], off offset:1024
.LBB0_138:
	s_or_b64 exec, exec, s[0:1]
	v_mov_b32_e32 v8, 0
	v_mov_b32_e32 v12, 0
	v_mov_b32_e32 v13, 0
	v_mov_b32_e32 v14, 0
	v_mov_b32_e32 v15, 0
	s_and_saveexec_b64 s[0:1], s[4:5]
	s_cbranch_execz .LBB0_140
	global_load_dwordx4 v[12:15], v[42:43], off offset:2048
.LBB0_140:
	s_or_b64 exec, exec, s[0:1]
	v_mov_b32_e32 v9, 0
	v_mov_b32_e32 v10, 0
	v_mov_b32_e32 v11, 0
	s_and_saveexec_b64 s[0:1], s[4:5]
	s_cbranch_execz .LBB0_142
	global_load_dwordx4 v[8:11], v[42:43], off offset:3072
.LBB0_142:
	s_or_b64 exec, exec, s[0:1]
	v_mov_b32_e32 v16, 0
	v_mov_b32_e32 v20, 0
	v_mov_b32_e32 v21, 0
	v_mov_b32_e32 v22, 0
	v_mov_b32_e32 v23, 0
	s_and_saveexec_b64 s[0:1], s[4:5]
	s_cbranch_execz .LBB0_144
	v_add_co_u32_e32 v18, vcc, 0x1000, v42
	s_nop 1
	v_addc_co_u32_e32 v19, vcc, 0, v43, vcc
	global_load_dwordx4 v[20:23], v[18:19], off
.LBB0_144:
	s_or_b64 exec, exec, s[0:1]
	v_mov_b32_e32 v17, 0
	v_mov_b32_e32 v18, 0
	v_mov_b32_e32 v19, 0
	s_and_saveexec_b64 s[0:1], s[4:5]
	s_cbranch_execz .LBB0_146
	v_add_co_u32_e32 v16, vcc, 0x1000, v42
	s_nop 1
	v_addc_co_u32_e32 v17, vcc, 0, v43, vcc
	global_load_dwordx4 v[16:19], v[16:17], off offset:1024
.LBB0_146:
	s_or_b64 exec, exec, s[0:1]
	v_mov_b32_e32 v24, 0
	v_mov_b32_e32 v28, 0
	v_mov_b32_e32 v29, 0
	v_mov_b32_e32 v30, 0
	v_mov_b32_e32 v31, 0
	s_and_saveexec_b64 s[0:1], s[4:5]
	s_cbranch_execz .LBB0_148
	v_add_co_u32_e32 v26, vcc, 0x1000, v42
	s_nop 1
	v_addc_co_u32_e32 v27, vcc, 0, v43, vcc
	global_load_dwordx4 v[28:31], v[26:27], off offset:2048
.LBB0_148:
	s_or_b64 exec, exec, s[0:1]
	v_mov_b32_e32 v25, 0
	v_mov_b32_e32 v26, 0
	v_mov_b32_e32 v27, 0
	s_and_saveexec_b64 s[0:1], s[4:5]
	s_cbranch_execz .LBB0_150
	v_add_co_u32_e32 v24, vcc, 0x1000, v42
	s_nop 1
	v_addc_co_u32_e32 v25, vcc, 0, v43, vcc
	global_load_dwordx4 v[24:27], v[24:25], off offset:3072
.LBB0_150:
	s_or_b64 exec, exec, s[0:1]
	s_waitcnt vmcnt(0)
	v_cvt_pk_bf16_f32 v200, v4, v5
	v_cvt_pk_bf16_f32 v201, v6, v7
	global_store_dwordx2 v[40:41], v[200:201], off
	v_cvt_pk_bf16_f32 v202, v0, v1
	v_cvt_pk_bf16_f32 v203, v2, v3
	global_store_dwordx2 v[40:41], v[202:203], off offset:512
	v_cvt_pk_bf16_f32 v204, v12, v13
	v_cvt_pk_bf16_f32 v205, v14, v15
	global_store_dwordx2 v[40:41], v[204:205], off offset:1024
	v_cvt_pk_bf16_f32 v206, v8, v9
	v_cvt_pk_bf16_f32 v207, v10, v11
	global_store_dwordx2 v[40:41], v[206:207], off offset:1536
	v_cvt_pk_bf16_f32 v208, v20, v21
	v_cvt_pk_bf16_f32 v209, v22, v23
	global_store_dwordx2 v[40:41], v[208:209], off offset:2048
	v_cvt_pk_bf16_f32 v210, v16, v17
	v_cvt_pk_bf16_f32 v211, v18, v19
	global_store_dwordx2 v[40:41], v[210:211], off offset:2560
	v_cvt_pk_bf16_f32 v212, v28, v29
	v_cvt_pk_bf16_f32 v213, v30, v31
	global_store_dwordx2 v[40:41], v[212:213], off offset:3072
	v_mul_f32_e32 v1, v1, v1
	v_mul_f32_e32 v5, v5, v5
	v_fmac_f32_e32 v1, v0, v0
	v_mul_f32_e32 v0, v3, v3
	v_fmac_f32_e32 v5, v4, v4
	v_mul_f32_e32 v4, v7, v7
	v_fmac_f32_e32 v0, v2, v2
	v_fmac_f32_e32 v4, v6, v6
	v_add_f32_e32 v0, v1, v0
	v_mul_f32_e32 v1, v13, v13
	v_mul_f32_e32 v2, v15, v15
	v_add_f32_e32 v4, v5, v4
	v_fmac_f32_e32 v1, v12, v12
	v_fmac_f32_e32 v2, v14, v14
	v_add_f32_e32 v0, v4, v0
	v_add_f32_e32 v1, v1, v2
	v_add_f32_e32 v0, v0, v1
	v_mul_f32_e32 v1, v9, v9
	v_mul_f32_e32 v2, v11, v11
	v_fmac_f32_e32 v1, v8, v8
	v_fmac_f32_e32 v2, v10, v10
	v_add_f32_e32 v1, v1, v2
	v_add_f32_e32 v0, v0, v1
	v_mul_f32_e32 v1, v21, v21
	v_mul_f32_e32 v2, v23, v23
	v_fmac_f32_e32 v1, v20, v20
	v_fmac_f32_e32 v2, v22, v22
	v_add_f32_e32 v1, v1, v2
	v_add_f32_e32 v0, v0, v1
	v_mul_f32_e32 v1, v17, v17
	v_mul_f32_e32 v2, v19, v19
	v_fmac_f32_e32 v1, v16, v16
	v_fmac_f32_e32 v2, v18, v18
	v_add_f32_e32 v1, v1, v2
	v_add_f32_e32 v0, v0, v1
	v_mul_f32_e32 v1, v29, v29
	v_mul_f32_e32 v2, v31, v31
	v_fmac_f32_e32 v1, v28, v28
	v_fmac_f32_e32 v2, v30, v30
	v_add_f32_e32 v1, v1, v2
	v_add_f32_e32 v0, v0, v1
	v_mul_f32_e32 v1, v25, v25
	v_mul_f32_e32 v2, v27, v27
	v_fmac_f32_e32 v1, v24, v24
	v_fmac_f32_e32 v2, v26, v26
	v_add_f32_e32 v1, v1, v2
	v_add_f32_e32 v0, v0, v1
	ds_bpermute_b32 v1, v44, v0
	v_cvt_pk_bf16_f32 v2, v24, v25
	v_cvt_pk_bf16_f32 v3, v26, v27
	global_store_dwordx2 v[40:41], v[2:3], off offset:3584
	s_waitcnt lgkmcnt(0)
	v_add_f32_e32 v0, v0, v1
	ds_bpermute_b32 v1, v45, v0
	s_waitcnt lgkmcnt(0)
	v_add_f32_e32 v0, v0, v1
	ds_bpermute_b32 v1, v46, v0
	s_waitcnt lgkmcnt(0)
	v_add_f32_e32 v0, v0, v1
	ds_bpermute_b32 v1, v47, v0
	s_waitcnt lgkmcnt(0)
	v_add_f32_e32 v0, v0, v1
	ds_bpermute_b32 v1, v48, v0
	s_waitcnt lgkmcnt(0)
	v_add_f32_e32 v0, v0, v1
	ds_bpermute_b32 v1, v49, v0
	s_and_saveexec_b64 s[0:1], s[2:3]
	s_cbranch_execz .LBB0_152
	s_waitcnt lgkmcnt(0)
	v_add_f32_e32 v2, v0, v1
	v_lshl_add_u64 v[0:1], v[38:39], 2, s[6:7]
	global_store_dword v[0:1], v2, off

; __device__ __forceinline__ void phase_prep(const Args& a, LAS unsigned char* lds, int G) {
;     ...
;     for (int jr = 0; jr < 4; ++jr) { const int r = rg * 32 + wid * 4 + jr;
;         const float* src = r >= ROW_X ? a.x + (size_t)(r - ROW_X) * DM : (r >= ROW_META ? a.meta + (size_t)(r - ROW_META) * DM : nullptr);
;         float s = 0.f;
; #pragma unroll
;         for (int j = 0; j < 8; ++j) { f32x4 v = src ? *(const f32x4*)(src + j * 256 + lane * 4) : (f32x4){0.f, 0.f, 0.f, 0.f};
.LBB0_156:
	s_or_b64 exec, exec, s[0:1]
	s_waitcnt lgkmcnt(0)
	v_cmp_ne_u64_e64 s[4:5], 0, v[0:1]
	v_lshl_add_u64 v[42:43], v[0:1], 0, v[32:33]
	v_ashrrev_i32_e32 v39, 31, v38
	v_lshlrev_b64 v[2:3], 12, v[38:39]
	v_lshl_add_u64 v[40:41], v[34:35], 0, v[2:3]
	v_mov_b32_e32 v0, 0
	v_mov_b32_e32 v4, 0
	v_mov_b32_e32 v5, 0
	v_mov_b32_e32 v6, 0
	v_mov_b32_e32 v7, 0
	s_and_saveexec_b64 s[0:1], s[4:5]
	s_cbranch_execz .LBB0_158
	global_load_dwordx4 v[4:7], v[42:43], off

; __device__ __forceinline__ void phase_prep(const Args& a, LAS unsigned char* lds, int G) {
;     ...
;         for (int j = 0; j < 8; ++j) { f32x4 v = src ? *(const f32x4*)(src + j * 256 + lane * 4) : (f32x4){0.f, 0.f, 0.f, 0.f};
;             u32x2 w; w.x = cvtpk(v[0], v[1]); w.y = cvtpk(v[2], v[3]); *(u32x2*)(HB + (size_t)r * DM + j * 256 + lane * 4) = w;
;             s += (v[0] * v[0] + v[1] * v[1]) + (v[2] * v[2] + v[3] * v[3]); }
;         s = wave_sum(s); if (lane == 0) ssq0[r] = s;
.LBB0_194:
	s_or_b64 exec, exec, s[0:1]
	s_waitcnt vmcnt(0)
	v_cvt_pk_bf16_f32 v200, v4, v5
	v_cvt_pk_bf16_f32 v201, v6, v7
	global_store_dwordx2 v[40:41], v[200:201], off
	v_cvt_pk_bf16_f32 v202, v0, v1
	v_cvt_pk_bf16_f32 v203, v2, v3
	global_store_dwordx2 v[40:41], v[202:203], off offset:512
	v_cvt_pk_bf16_f32 v204, v12, v13
	v_cvt_pk_bf16_f32 v205, v14, v15
	global_store_dwordx2 v[40:41], v[204:205], off offset:1024
	v_cvt_pk_bf16_f32 v206, v8, v9
	v_cvt_pk_bf16_f32 v207, v10, v11
	global_store_dwordx2 v[40:41], v[206:207], off offset:1536
	v_cvt_pk_bf16_f32 v208, v20, v21
	v_cvt_pk_bf16_f32 v209, v22, v23
	global_store_dwordx2 v[40:41], v[208:209], off offset:2048
	v_cvt_pk_bf16_f32 v210, v16, v17
	v_cvt_pk_bf16_f32 v211, v18, v19
	global_store_dwordx2 v[40:41], v[210:211], off offset:2560
	v_cvt_pk_bf16_f32 v212, v28, v29
	v_cvt_pk_bf16_f32 v213, v30, v31
	global_store_dwordx2 v[40:41], v[212:213], off offset:3072
	v_mul_f32_e32 v1, v1, v1
	v_mul_f32_e32 v5, v5, v5
	v_fmac_f32_e32 v1, v0, v0
	v_mul_f32_e32 v0, v3, v3
	v_fmac_f32_e32 v5, v4, v4
	v_mul_f32_e32 v4, v7, v7
	v_fmac_f32_e32 v0, v2, v2
	v_fmac_f32_e32 v4, v6, v6
	v_add_f32_e32 v0, v1, v0
	v_mul_f32_e32 v1, v13, v13
	v_mul_f32_e32 v2, v15, v15
	v_add_f32_e32 v4, v5, v4
	v_fmac_f32_e32 v1, v12, v12
	v_fmac_f32_e32 v2, v14, v14
	v_add_f32_e32 v0, v4, v0
	v_add_f32_e32 v1, v1, v2
	v_add_f32_e32 v0, v0, v1
	v_mul_f32_e32 v1, v9, v9
	v_mul_f32_e32 v2, v11, v11
	v_fmac_f32_e32 v1, v8, v8
	v_fmac_f32_e32 v2, v10, v10
	v_add_f32_e32 v1, v1, v2
	v_add_f32_e32 v0, v0, v1
	v_mul_f32_e32 v1, v21, v21
	v_mul_f32_e32 v2, v23, v23
	v_fmac_f32_e32 v1, v20, v20
	v_fmac_f32_e32 v2, v22, v22
	v_add_f32_e32 v1, v1, v2
	v_add_f32_e32 v0, v0, v1
	v_mul_f32_e32 v1, v17, v17
	v_mul_f32_e32 v2, v19, v19
	v_fmac_f32_e32 v1, v16, v16
	v_fmac_f32_e32 v2, v18, v18
	v_add_f32_e32 v1, v1, v2
	v_add_f32_e32 v0, v0, v1
	v_mul_f32_e32 v1, v29, v29
	v_mul_f32_e32 v2, v31, v31
	v_fmac_f32_e32 v1, v28, v28
	v_fmac_f32_e32 v2, v30, v30
	v_add_f32_e32 v1, v1, v2
	v_add_f32_e32 v0, v0, v1
	v_mul_f32_e32 v1, v25, v25
	v_mul_f32_e32 v2, v27, v27
	v_fmac_f32_e32 v1, v24, v24
	v_fmac_f32_e32 v2, v26, v26
	v_add_f32_e32 v1, v1, v2
	v_add_f32_e32 v0, v0, v1
	ds_bpermute_b32 v1, v44, v0
	v_cvt_pk_bf16_f32 v2, v24, v25
	v_cvt_pk_bf16_f32 v3, v26, v27
	global_store_dwordx2 v[40:41], v[2:3], off offset:3584
	s_waitcnt lgkmcnt(0)
	v_add_f32_e32 v0, v0, v1
	ds_bpermute_b32 v1, v45, v0
	s_waitcnt lgkmcnt(0)
	v_add_f32_e32 v0, v0, v1
	ds_bpermute_b32 v1, v46, v0
	s_waitcnt lgkmcnt(0)
	v_add_f32_e32 v0, v0, v1
	ds_bpermute_b32 v1, v47, v0
	s_waitcnt lgkmcnt(0)
	v_add_f32_e32 v0, v0, v1
	ds_bpermute_b32 v1, v48, v0
	s_waitcnt lgkmcnt(0)
	v_add_f32_e32 v0, v0, v1
	ds_bpermute_b32 v1, v49, v0
	s_and_saveexec_b64 s[0:1], s[2:3]
	s_cbranch_execz .LBB0_107
	s_waitcnt lgkmcnt(0)
	v_add_f32_e32 v2, v0, v1
	v_lshl_add_u64 v[0:1], v[38:39], 2, s[6:7]
	global_store_dword v[0:1], v2, off
	s_branch .LBB0_107
